# sliding-window prompt units: K/V staging loads 2..6 issued early as prefetch ahead of the serial load-wait-write chain
# speedup vs baseline: 1.0054x; 1.0054x over previous
.LBB0_865:
	s_and_b32 s82, s76, 31
	s_lshl_b32 s78, s82, 6
	s_add_i32 s34, s78, 0xffffff80
	s_ashr_i32 s80, s76, 8
	s_bfe_u32 s77, s76, 0x30005
	v_or_b32_e32 v6, s34, v96
	s_lshl_b32 s79, s80, 11
	s_lshl_b32 s81, s77, 6
	s_lshl_b32 s16, s81, 1
	v_add_u32_e32 v4, s34, v97
	v_cmp_lt_i32_e32 vcc, -1, v4
	s_and_saveexec_b64 s[8:9], vcc
	s_cbranch_execz .Lswp_k1
	v_add_u32_e32 v4, s79, v4
	v_mov_b64_e32 v[2:3], s[18:19]
	v_mad_i64_i32 v[2:3], s[40:41], v4, s43, v[2:3]
	v_mov_b32_e32 v4, v86
	v_mov_b32_e32 v5, 0
	v_lshl_add_u64 v[2:3], v[2:3], 0, s[16:17]
	v_lshl_add_u64 v[2:3], v[2:3], 0, v[4:5]
	v_add_co_u32_e32 v2, vcc, 0x2000, v2
	s_nop 1
	v_addc_co_u32_e32 v3, vcc, 0, v3, vcc
	global_load_dwordx4 v[8:11], v[2:3], off
.Lswp_k1:
	s_or_b64 exec, exec, s[8:9]
	v_or_b32_e32 v4, s79, v98
	v_add_u32_e32 v4, s34, v4
	v_mov_b64_e32 v[2:3], s[18:19]
	v_mad_i64_i32 v[2:3], s[40:41], v4, s43, v[2:3]
	v_mov_b32_e32 v4, v86
	v_mov_b32_e32 v5, 0
	v_lshl_add_u64 v[2:3], v[2:3], 0, s[16:17]
	v_lshl_add_u64 v[2:3], v[2:3], 0, v[4:5]
	v_add_co_u32_e32 v2, vcc, 0x2000, v2
	s_nop 1
	v_addc_co_u32_e32 v3, vcc, 0, v3, vcc
	global_load_dwordx4 v[8:11], v[2:3], off
	v_add_u32_e32 v4, s34, v99
	v_cmp_lt_i32_e32 vcc, -1, v4
	s_and_saveexec_b64 s[8:9], vcc
	s_cbranch_execz .Lswp_v0
	v_add_u32_e32 v4, s79, v4
	v_mov_b64_e32 v[2:3], s[18:19]
	v_mad_i64_i32 v[2:3], s[40:41], v4, s43, v[2:3]
	v_mov_b32_e32 v4, v88
	v_mov_b32_e32 v5, 0
	v_lshl_add_u64 v[2:3], v[2:3], 0, s[16:17]
	v_lshl_add_u64 v[2:3], v[2:3], 0, v[4:5]
	v_add_co_u32_e32 v2, vcc, 0x2000, v2
	s_nop 1
	v_addc_co_u32_e32 v3, vcc, 0, v3, vcc
	global_load_dwordx4 v[8:11], v[2:3], off offset:1024
.Lswp_v0:
	s_or_b64 exec, exec, s[8:9]
	v_add_u32_e32 v4, s34, v100
	v_cmp_lt_i32_e32 vcc, -1, v4
	s_and_saveexec_b64 s[8:9], vcc
	s_cbranch_execz .Lswp_v1
	v_add_u32_e32 v4, s79, v4
	v_mov_b64_e32 v[2:3], s[18:19]
	v_mad_i64_i32 v[2:3], s[40:41], v4, s43, v[2:3]
	v_mov_b32_e32 v4, v90
	v_mov_b32_e32 v5, 0
	v_lshl_add_u64 v[2:3], v[2:3], 0, s[16:17]
	v_lshl_add_u64 v[2:3], v[2:3], 0, v[4:5]
	v_add_co_u32_e32 v2, vcc, 0x2000, v2
	s_nop 1
	v_addc_co_u32_e32 v3, vcc, 0, v3, vcc
	global_load_dwordx4 v[8:11], v[2:3], off offset:1024
.Lswp_v1:
	s_or_b64 exec, exec, s[8:9]
	v_add_u32_e32 v4, s34, v101
	v_cmp_lt_i32_e32 vcc, -1, v4
	s_and_saveexec_b64 s[8:9], vcc
	s_cbranch_execz .Lswp_v2
	v_add_u32_e32 v4, s79, v4
	v_mov_b64_e32 v[2:3], s[18:19]
	v_mad_i64_i32 v[2:3], s[40:41], v4, s43, v[2:3]
	v_mov_b32_e32 v4, v92
	v_mov_b32_e32 v5, 0
	v_lshl_add_u64 v[2:3], v[2:3], 0, s[16:17]
	v_lshl_add_u64 v[2:3], v[2:3], 0, v[4:5]
	v_add_co_u32_e32 v2, vcc, 0x2000, v2
	s_nop 1
	v_addc_co_u32_e32 v3, vcc, 0, v3, vcc
	global_load_dwordx4 v[8:11], v[2:3], off offset:1024
.Lswp_v2:
	s_or_b64 exec, exec, s[8:9]
	v_cmp_lt_i32_e32 vcc, -1, v6
	v_mov_b32_e32 v2, v83
	v_mov_b32_e32 v3, v83
	v_mov_b32_e32 v4, v83
	v_mov_b32_e32 v5, v83
	s_and_saveexec_b64 s[8:9], vcc
	s_cbranch_execz .LBB0_867
	v_add_u32_e32 v4, s79, v6
	v_mov_b64_e32 v[2:3], s[18:19]
	v_mad_i64_i32 v[2:3], s[40:41], v4, s43, v[2:3]
	s_lshl_b32 s16, s81, 1
	v_lshl_add_u64 v[2:3], v[2:3], 0, s[16:17]
	v_mov_b32_e32 v87, v83
	v_lshl_add_u64 v[2:3], v[2:3], 0, v[86:87]
	v_add_co_u32_e32 v2, vcc, 0x2000, v2
	s_nop 1
	v_addc_co_u32_e32 v3, vcc, 0, v3, vcc
	global_load_dwordx4 v[2:5], v[2:3], off
